# cp_load/cp_store address math rewritten without integer division in P1 and S4 epilogues; vmcnt waits relaxed
# speedup vs baseline: 1.0165x; 1.0095x over previous
.LBB0_994:
	s_sub_i32 s1, s58, s6
	s_mul_i32 s1, s1, 22
	s_add_i32 s1, s0, s1
	s_add_i32 s1, s1, 22
	s_ashr_i32 s1, s1, 2
	s_and_b32 s37, s1, 1
	s_lshl_b32 s2, s37, 2
	v_lshl_add_u32 v210, s6, 8, v212
	s_add_i32 s2, s2, 0
	s_add_i32 s2, s2, 0x201a0
	v_or_b32_e32 v208, 16, v210
	v_mov_b32_e32 v66, s2
	v_ashrrev_i32_e32 v211, 31, v210
	v_ashrrev_i32_e32 v209, 31, v208
	ds_read_b32 v146, v66
	v_lshlrev_b64 v[66:67], 6, v[210:211]
	v_lshlrev_b64 v[68:69], 6, v[208:209]
	v_or_b32_e32 v206, 32, v210
	v_or_b32_e32 v204, 48, v210
	v_lshl_add_u64 v[66:67], v[190:191], 0, v[66:67]
	v_lshl_add_u64 v[68:69], v[190:191], 0, v[68:69]
	v_ashrrev_i32_e32 v207, 31, v206
	v_ashrrev_i32_e32 v205, 31, v204
	global_load_dwordx4 v[174:177], v[66:67], off
	global_load_dwordx4 v[170:173], v[68:69], off
	v_lshlrev_b64 v[66:67], 6, v[206:207]
	v_lshlrev_b64 v[68:69], 6, v[204:205]
	v_add_u32_e32 v202, 0x80, v210
	v_add_u32_e32 v200, 0x90, v210
	v_lshl_add_u64 v[66:67], v[190:191], 0, v[66:67]
	v_lshl_add_u64 v[68:69], v[190:191], 0, v[68:69]
	v_ashrrev_i32_e32 v203, 31, v202
	v_ashrrev_i32_e32 v201, 31, v200
	global_load_dwordx4 v[166:169], v[66:67], off
	global_load_dwordx4 v[162:165], v[68:69], off
	v_lshlrev_b64 v[66:67], 6, v[202:203]
	v_lshlrev_b64 v[68:69], 6, v[200:201]
	v_add_u32_e32 v198, 0xa0, v210
	v_add_u32_e32 v196, 0xb0, v210
	v_lshl_add_u64 v[66:67], v[190:191], 0, v[66:67]
	v_lshl_add_u64 v[68:69], v[190:191], 0, v[68:69]
	v_ashrrev_i32_e32 v199, 31, v198
	v_ashrrev_i32_e32 v197, 31, v196
	global_load_dwordx4 v[106:109], v[66:67], off
	global_load_dwordx4 v[86:89], v[68:69], off
	v_lshlrev_b64 v[66:67], 6, v[198:199]
	v_lshlrev_b64 v[68:69], 6, v[196:197]
	v_lshl_add_u64 v[66:67], v[190:191], 0, v[66:67]
	v_lshl_add_u64 v[68:69], v[190:191], 0, v[68:69]
	global_load_dwordx4 v[70:73], v[66:67], off
	s_nop 0
	global_load_dwordx4 v[66:69], v[68:69], off
	s_waitcnt lgkmcnt(0)
	v_readfirstlane_b32 s2, v146
	v_cmp_lt_i32_e32 vcc, s66, v146
	v_mov_b32_e32 v153, 0
	v_cmp_gt_i32_e64 s[6:7], s65, v146
	s_and_b64 vcc, exec, vcc
	v_mov_b32_e32 v152, 0
	v_mov_b32_e32 v151, 0
	v_mov_b32_e32 v150, 0
	v_mov_b32_e32 v157, 0
	v_mov_b32_e32 v156, 0
	v_mov_b32_e32 v155, 0
	v_mov_b32_e32 v154, 0
	v_mov_b32_e32 v149, 0
	v_mov_b32_e32 v148, 0
	v_mov_b32_e32 v147, 0
	v_mov_b32_e32 v146, 0
	v_mov_b32_e32 v161, 0
	v_mov_b32_e32 v160, 0
	v_mov_b32_e32 v159, 0
	v_mov_b32_e32 v158, 0
	s_cbranch_vccnz .Ls4_nocp
	s_cmpk_lt_u32 s2, 0xf8
	s_cbranch_scc0 .Lcpl4_a
	s_mov_b32 s4, s2
	s_mov_b32 s5, 0x8421085
	s_movk_i32 s22, 0x3e00
	s_movk_i32 s39, 0x200
	s_mov_b64 s[8:9], s[12:13]
	s_add_u32 s100, s20, 0x8280000
	s_addc_u32 s101, s21, 0
	s_branch .Lcpl4_go
.Lcpl4_a:
	s_cmpk_lt_u32 s2, 0x4f0
	s_cbranch_scc0 .Lcpl4_b
	s_add_i32 s4, s2, 0xffffff08
	s_mov_b32 s5, 0x2040811
	s_mov_b32 s22, 0xfe00
	s_movk_i32 s39, 0x200
	s_mov_b64 s[8:9], s[14:15]
	s_add_u32 s100, s20, 0x9280000
	s_addc_u32 s101, s21, 0
	s_branch .Lcpl4_go
.Lcpl4_b:
	s_cmpk_lt_u32 s2, 0x14e8
	s_cbranch_scc0 .Lcpl4_c
	s_add_i32 s4, s2, 0xfffffb10
	s_mov_b32 s5, 0x804021
	s_mov_b32 s22, 0x3fe00
	s_movk_i32 s39, 0x200
	s_mov_b64 s[8:9], s[16:17]
	s_add_u32 s100, s20, 0xd280000
	s_addc_u32 s101, s21, 0
	s_branch .Lcpl4_go
.Lcpl4_c:
	s_add_i32 s4, s2, 0xffffeb18
	s_mov_b32 s5, 0x13b13b14
	s_movk_i32 s22, 0x1a00
	s_movk_i32 s39, 0x400
	s_mov_b64 s[8:9], s[18:19]
	s_add_u32 s100, s20, 0x15370000
	s_addc_u32 s101, s21, 0
.Lcpl4_go:
	s_lshl_b32 s3, s4, 2
	s_mul_hi_u32 s3, s3, s5
	s_lshl_b32 s4, s4, 11
	s_mul_i32 s10, s3, s22
	s_sub_u32 s10, s4, s10
	s_mul_i32 s11, s3, s39
	s_add_u32 s11, s4, s11
	v_add_u32_e32 v146, s10, v215
	v_add_u32_e32 v154, s10, v216
	v_add_u32_e32 v150, s10, v217
	v_add_u32_e32 v158, s10, v218
	v_cmp_le_u32_e64 s[44:45], s22, v146
	v_cmp_le_u32_e64 s[46:47], s22, v154
	v_cmp_le_u32_e64 s[74:75], s22, v150
	v_cmp_le_u32_e64 vcc, s22, v158
	v_add_u32_e32 v146, s11, v215
	v_add_u32_e32 v154, s11, v216
	v_add_u32_e32 v150, s11, v217
	v_add_u32_e32 v158, s11, v218
	v_mov_b32_e32 v148, s39
	v_cndmask_b32_e64 v147, 0, v148, s[44:45]
	v_cndmask_b32_e64 v155, 0, v148, s[46:47]
	v_cndmask_b32_e64 v151, 0, v148, s[74:75]
	v_cndmask_b32_e64 v159, 0, v148, vcc
	v_add_u32_e32 v146, v146, v147
	v_add_u32_e32 v154, v154, v155
	v_add_u32_e32 v150, v150, v151
	v_add_u32_e32 v158, v158, v159
	v_mov_b32_e32 v147, 0
	v_mov_b32_e32 v155, 0
	v_mov_b32_e32 v151, 0
	v_mov_b32_e32 v159, 0
	v_lshl_add_u64 v[248:249], v[146:147], 4, s[100:101]
	v_lshl_add_u64 v[250:251], v[154:155], 4, s[100:101]
	v_lshl_add_u64 v[252:253], v[150:151], 4, s[100:101]
	v_lshl_add_u64 v[254:255], v[158:159], 4, s[100:101]
	v_add_u32_e32 v146, s39, v146
	v_add_u32_e32 v154, s39, v154
	v_add_u32_e32 v150, s39, v150
	v_add_u32_e32 v158, s39, v158
	v_lshl_add_u64 v[146:147], v[146:147], 4, s[8:9]
	v_lshl_add_u64 v[154:155], v[154:155], 4, s[8:9]
	v_lshl_add_u64 v[150:151], v[150:151], 4, s[8:9]
	v_lshl_add_u64 v[158:159], v[158:159], 4, s[8:9]
	global_load_dwordx4 v[146:149], v[146:147], off nt
	global_load_dwordx4 v[154:157], v[154:155], off nt
	global_load_dwordx4 v[150:153], v[150:151], off nt
	global_load_dwordx4 v[158:161], v[158:159], off nt
	s_branch .LBB0_1012

.LBB0_1012:
	v_lshl_or_b32 v224, s0, 7, v214
	v_and_b32_e32 v197, 64, v181
	v_xor_b32_e32 v199, 16, v181
	v_add_u32_e32 v197, 64, v197
	v_cmp_lt_i32_e32 vcc, v199, v197
	s_waitcnt vmcnt(4)
	v_mov_b32_e32 v226, v175
	v_mov_b32_e32 v227, v176
	v_mov_b32_e32 v175, v177
	v_cndmask_b32_e32 v199, v181, v199, vcc
	v_pk_add_f32 v[174:175], v[226:227], v[174:175]
	v_lshlrev_b32_e32 v199, 2, v199
	v_add_f32_e32 v175, v174, v175
	ds_bpermute_b32 v176, v199, v175
	v_xor_b32_e32 v174, 32, v181
	v_cmp_lt_i32_e32 vcc, v174, v197
	v_ashrrev_i32_e32 v225, 31, v224
	s_waitcnt lgkmcnt(0)
	v_add_f32_e32 v175, v175, v176
	v_cndmask_b32_e32 v174, v181, v174, vcc
	v_lshlrev_b32_e32 v174, 2, v174
	ds_bpermute_b32 v176, v174, v175
	s_waitcnt lgkmcnt(0)
	v_add_f32_e32 v175, v175, v176
	v_fmamk_f32 v175, v175, 0x3a800000, v222
	v_rsq_f32_e32 v176, v175
	s_nop 0
	v_pk_mul_f32 v[142:143], v[142:143], v[176:177] op_sel_hi:[1,0]
	s_nop 0
	v_mul_f32_e32 v175, 0xbfb8aa3b, v142
	v_mul_f32_e32 v177, 0xbfb8aa3b, v143
	v_exp_f32_e32 v175, v175
	v_exp_f32_e32 v177, v177
	v_add_f32_e32 v175, 1.0, v175
	v_add_f32_e32 v177, 1.0, v177
	v_rcp_f32_e32 v226, v175
	v_rcp_f32_e32 v227, v177
	v_pk_mul_f32 v[144:145], v[144:145], v[176:177] op_sel_hi:[1,0]
	v_pk_mul_f32 v[138:139], v[138:139], v[176:177] op_sel_hi:[1,0]
	v_mul_f32_e32 v175, 0xbfb8aa3b, v144
	v_pk_mul_f32 v[142:143], v[142:143], v[226:227]
	v_exp_f32_e32 v175, v175
	v_pk_mul_f32 v[138:139], v[138:139], v[142:143]
	v_mul_f32_e32 v142, 0xbfb8aa3b, v145
	v_exp_f32_e32 v143, v142
	v_pk_mul_f32 v[134:135], v[134:135], v[176:177] op_sel_hi:[1,0]
	v_add_f32_e32 v142, 1.0, v175
	v_mul_f32_e32 v175, 0xbfb8aa3b, v134
	v_pk_mul_f32 v[140:141], v[140:141], v[176:177] op_sel_hi:[1,0]
	v_add_f32_e32 v143, 1.0, v143
	v_exp_f32_e32 v175, v175
	v_mul_f32_e32 v177, 0xbfb8aa3b, v135
	v_rcp_f32_e32 v142, v142
	v_exp_f32_e32 v177, v177
	v_rcp_f32_e32 v143, v143
	v_add_f32_e32 v175, 1.0, v175
	v_rcp_f32_e32 v226, v175
	v_add_f32_e32 v175, 1.0, v177
	v_pk_mul_f32 v[142:143], v[144:145], v[142:143]
	v_pk_mul_f32 v[136:137], v[136:137], v[176:177] op_sel_hi:[1,0]
	v_rcp_f32_e32 v227, v175
	v_pk_mul_f32 v[140:141], v[140:141], v[142:143]
	v_mul_f32_e32 v142, 0xbfb8aa3b, v136
	v_mul_f32_e32 v143, 0xbfb8aa3b, v137
	v_exp_f32_e32 v142, v142
	v_exp_f32_e32 v143, v143
	v_pk_mul_f32 v[130:131], v[130:131], v[176:177] op_sel_hi:[1,0]
	v_pk_mul_f32 v[134:135], v[134:135], v[226:227]
	v_pk_mul_f32 v[132:133], v[132:133], v[176:177] op_sel_hi:[1,0]
	v_pk_mul_f32 v[130:131], v[130:131], v[134:135]
	v_add_f32_e32 v134, 1.0, v142
	v_add_f32_e32 v135, 1.0, v143
	v_mov_b32_e32 v142, v171
	v_mov_b32_e32 v143, v172
	v_mov_b32_e32 v171, v173
	v_pk_add_f32 v[142:143], v[142:143], v[170:171]
	v_rcp_f32_e32 v134, v134
	v_add_f32_e32 v142, v142, v143
	v_rcp_f32_e32 v135, v135
	ds_bpermute_b32 v143, v199, v142
	v_pk_mul_f32 v[134:135], v[136:137], v[134:135]
	s_nop 0
	v_pk_mul_f32 v[132:133], v[132:133], v[134:135]
	v_cvt_pk_bf16_f32 v134, v138, v139
	s_waitcnt lgkmcnt(0)
	v_add_f32_e32 v138, v142, v143
	ds_bpermute_b32 v139, v174, v138
	v_cvt_pk_bf16_f32 v136, v130, v131
	v_cvt_pk_bf16_f32 v137, v132, v133
	v_mov_b64_e32 v[132:133], s[26:27]
	v_cvt_pk_bf16_f32 v135, v140, v141
	s_waitcnt lgkmcnt(0)
	v_add_f32_e32 v130, v138, v139
	v_fmamk_f32 v130, v130, 0x3a800000, v222
	v_rsq_f32_e32 v138, v130
	v_mad_i64_i32 v[140:141], s[4:5], v210, s68, v[132:133]
	v_lshlrev_b64 v[130:131], 1, v[224:225]
	v_pk_mul_f32 v[126:127], v[126:127], v[138:139] op_sel_hi:[1,0]
	v_lshl_add_u64 v[140:141], v[140:141], 0, v[130:131]
	v_mul_f32_e32 v139, 0xbfb8aa3b, v126
	v_exp_f32_e32 v139, v139
	global_store_dwordx4 v[140:141], v[134:137], off
	v_pk_mul_f32 v[128:129], v[128:129], v[138:139] op_sel_hi:[1,0]
	s_nop 0
	v_mul_f32_e32 v134, 0xbfb8aa3b, v127
	v_exp_f32_e32 v135, v134
	v_mul_f32_e32 v136, 0xbfb8aa3b, v128
	v_mul_f32_e32 v137, 0xbfb8aa3b, v129
	v_exp_f32_e32 v136, v136
	v_exp_f32_e32 v137, v137
	v_add_f32_e32 v134, 1.0, v139
	v_add_f32_e32 v135, 1.0, v135
	v_rcp_f32_e32 v134, v134
	v_rcp_f32_e32 v135, v135
	v_add_f32_e32 v136, 1.0, v136
	v_add_f32_e32 v137, 1.0, v137
	v_rcp_f32_e32 v136, v136
	v_rcp_f32_e32 v137, v137
	v_pk_mul_f32 v[118:119], v[118:119], v[138:139] op_sel_hi:[1,0]
	v_pk_mul_f32 v[126:127], v[126:127], v[134:135]
	v_pk_mul_f32 v[120:121], v[120:121], v[138:139] op_sel_hi:[1,0]
	v_pk_mul_f32 v[118:119], v[118:119], v[126:127]
	v_pk_mul_f32 v[126:127], v[128:129], v[136:137]
	v_pk_mul_f32 v[122:123], v[122:123], v[138:139] op_sel_hi:[1,0]
	v_pk_mul_f32 v[120:121], v[120:121], v[126:127]
	v_mul_f32_e32 v128, 0xbfb8aa3b, v122
	v_mul_f32_e32 v126, 0xbfb8aa3b, v123
	v_exp_f32_e32 v128, v128
	v_exp_f32_e32 v127, v126
	v_pk_mul_f32 v[124:125], v[124:125], v[138:139] op_sel_hi:[1,0]
	v_pk_mul_f32 v[114:115], v[114:115], v[138:139] op_sel_hi:[1,0]
	v_add_f32_e32 v126, 1.0, v128
	v_add_f32_e32 v127, 1.0, v127
	v_mul_f32_e32 v128, 0xbfb8aa3b, v124
	v_mul_f32_e32 v129, 0xbfb8aa3b, v125
	v_rcp_f32_e32 v126, v126
	v_rcp_f32_e32 v127, v127
	v_exp_f32_e32 v128, v128
	v_exp_f32_e32 v129, v129
	v_pk_mul_f32 v[122:123], v[122:123], v[126:127]
	v_add_f32_e32 v126, 1.0, v128
	v_add_f32_e32 v127, 1.0, v129
	v_mov_b32_e32 v128, v167
	v_mov_b32_e32 v129, v168
	v_mov_b32_e32 v167, v169
	v_pk_add_f32 v[128:129], v[128:129], v[166:167]
	v_rcp_f32_e32 v126, v126
	v_add_f32_e32 v128, v128, v129
	ds_bpermute_b32 v129, v199, v128
	v_rcp_f32_e32 v127, v127
	v_pk_mul_f32 v[122:123], v[114:115], v[122:123]
	v_pk_mul_f32 v[114:115], v[116:117], v[138:139] op_sel_hi:[1,0]
	v_pk_mul_f32 v[116:117], v[124:125], v[126:127]
	s_waitcnt lgkmcnt(0)
	v_add_f32_e32 v126, v128, v129
	ds_bpermute_b32 v127, v174, v126
	v_pk_mul_f32 v[124:125], v[114:115], v[116:117]
	v_cvt_pk_bf16_f32 v114, v118, v119
	v_cvt_pk_bf16_f32 v115, v120, v121
	v_mad_i64_i32 v[120:121], s[4:5], v208, s68, v[132:133]
	s_waitcnt lgkmcnt(0)
	v_add_f32_e32 v118, v126, v127
	v_fmamk_f32 v118, v118, 0x3a800000, v222
	v_rsq_f32_e32 v118, v118
	v_cvt_pk_bf16_f32 v116, v122, v123
	v_cvt_pk_bf16_f32 v117, v124, v125
	v_lshl_add_u64 v[120:121], v[120:121], 0, v[130:131]
	v_pk_mul_f32 v[110:111], v[110:111], v[118:119] op_sel_hi:[1,0]
	global_store_dwordx4 v[120:121], v[114:117], off
	v_mul_f32_e32 v119, 0xbfb8aa3b, v110
	v_exp_f32_e32 v119, v119
	v_mul_f32_e32 v114, 0xbfb8aa3b, v111
	v_exp_f32_e32 v115, v114
	v_pk_mul_f32 v[112:113], v[112:113], v[118:119] op_sel_hi:[1,0]
	s_nop 0
	v_mul_f32_e32 v116, 0xbfb8aa3b, v112
	v_mul_f32_e32 v117, 0xbfb8aa3b, v113
	v_exp_f32_e32 v116, v116
	v_exp_f32_e32 v117, v117
	v_add_f32_e32 v114, 1.0, v119
	v_add_f32_e32 v115, 1.0, v115
	v_rcp_f32_e32 v114, v114
	v_rcp_f32_e32 v115, v115
	v_add_f32_e32 v116, 1.0, v116
	v_add_f32_e32 v117, 1.0, v117
	v_rcp_f32_e32 v116, v116
	v_rcp_f32_e32 v117, v117
	v_pk_mul_f32 v[98:99], v[98:99], v[118:119] op_sel_hi:[1,0]
	v_pk_mul_f32 v[110:111], v[110:111], v[114:115]
	v_pk_mul_f32 v[100:101], v[100:101], v[118:119] op_sel_hi:[1,0]
	v_pk_mul_f32 v[98:99], v[98:99], v[110:111]
	v_pk_mul_f32 v[110:111], v[112:113], v[116:117]
	v_pk_mul_f32 v[102:103], v[102:103], v[118:119] op_sel_hi:[1,0]
	v_pk_mul_f32 v[100:101], v[100:101], v[110:111]
	v_mul_f32_e32 v112, 0xbfb8aa3b, v102
	v_mul_f32_e32 v110, 0xbfb8aa3b, v103
	v_exp_f32_e32 v112, v112
	v_exp_f32_e32 v111, v110
	v_pk_mul_f32 v[104:105], v[104:105], v[118:119] op_sel_hi:[1,0]
	v_pk_mul_f32 v[94:95], v[94:95], v[118:119] op_sel_hi:[1,0]
	v_add_f32_e32 v110, 1.0, v112
	v_add_f32_e32 v111, 1.0, v111
	v_mul_f32_e32 v112, 0xbfb8aa3b, v104
	v_mul_f32_e32 v113, 0xbfb8aa3b, v105
	v_rcp_f32_e32 v110, v110
	v_rcp_f32_e32 v111, v111
	v_exp_f32_e32 v112, v112
	v_exp_f32_e32 v113, v113
	v_pk_mul_f32 v[102:103], v[102:103], v[110:111]
	v_add_f32_e32 v110, 1.0, v112
	v_add_f32_e32 v111, 1.0, v113
	v_mov_b32_e32 v112, v163
	v_mov_b32_e32 v113, v164
	v_mov_b32_e32 v163, v165
	v_pk_add_f32 v[112:113], v[112:113], v[162:163]
	v_rcp_f32_e32 v110, v110
	v_add_f32_e32 v112, v112, v113
	ds_bpermute_b32 v113, v199, v112
	v_rcp_f32_e32 v111, v111
	v_pk_mul_f32 v[102:103], v[94:95], v[102:103]
	v_pk_mul_f32 v[94:95], v[96:97], v[118:119] op_sel_hi:[1,0]
	v_pk_mul_f32 v[96:97], v[104:105], v[110:111]
	s_waitcnt lgkmcnt(0)
	v_add_f32_e32 v110, v112, v113
	ds_bpermute_b32 v111, v174, v110
	v_pk_mul_f32 v[104:105], v[94:95], v[96:97]
	v_cvt_pk_bf16_f32 v94, v98, v99
	v_cvt_pk_bf16_f32 v95, v100, v101
	v_mad_i64_i32 v[100:101], s[4:5], v206, s68, v[132:133]
	s_waitcnt lgkmcnt(0)
	v_add_f32_e32 v98, v110, v111
	v_fmamk_f32 v98, v98, 0x3a800000, v222
	v_rsq_f32_e32 v98, v98
	v_cvt_pk_bf16_f32 v96, v102, v103
	v_cvt_pk_bf16_f32 v97, v104, v105
	v_lshl_add_u64 v[100:101], v[100:101], 0, v[130:131]
	v_pk_mul_f32 v[90:91], v[90:91], v[98:99] op_sel_hi:[1,0]
	global_store_dwordx4 v[100:101], v[94:97], off
	v_mul_f32_e32 v99, 0xbfb8aa3b, v90
	v_exp_f32_e32 v99, v99
	v_mul_f32_e32 v94, 0xbfb8aa3b, v91
	v_exp_f32_e32 v95, v94
	v_pk_mul_f32 v[92:93], v[92:93], v[98:99] op_sel_hi:[1,0]
	s_nop 0
	v_mul_f32_e32 v96, 0xbfb8aa3b, v92
	v_mul_f32_e32 v97, 0xbfb8aa3b, v93
	v_exp_f32_e32 v96, v96
	v_exp_f32_e32 v97, v97
	v_add_f32_e32 v94, 1.0, v99
	v_add_f32_e32 v95, 1.0, v95
	v_rcp_f32_e32 v94, v94
	v_rcp_f32_e32 v95, v95
	v_add_f32_e32 v96, 1.0, v96
	v_add_f32_e32 v97, 1.0, v97
	v_rcp_f32_e32 v96, v96
	v_rcp_f32_e32 v97, v97
	v_pk_mul_f32 v[78:79], v[78:79], v[98:99] op_sel_hi:[1,0]
	v_pk_mul_f32 v[90:91], v[90:91], v[94:95]
	v_pk_mul_f32 v[82:83], v[82:83], v[98:99] op_sel_hi:[1,0]
	v_pk_mul_f32 v[78:79], v[78:79], v[90:91]
	v_pk_mul_f32 v[90:91], v[92:93], v[96:97]
	v_mul_f32_e32 v92, 0xbfb8aa3b, v82
	v_exp_f32_e32 v92, v92
	v_pk_mul_f32 v[80:81], v[80:81], v[98:99] op_sel_hi:[1,0]
	v_pk_mul_f32 v[84:85], v[84:85], v[98:99] op_sel_hi:[1,0]
	v_pk_mul_f32 v[80:81], v[80:81], v[90:91]
	v_mul_f32_e32 v90, 0xbfb8aa3b, v83
	v_exp_f32_e32 v91, v90
	v_add_f32_e32 v90, 1.0, v92
	v_mul_f32_e32 v92, 0xbfb8aa3b, v84
	v_mul_f32_e32 v93, 0xbfb8aa3b, v85
	v_exp_f32_e32 v92, v92
	v_exp_f32_e32 v93, v93
	v_add_f32_e32 v91, 1.0, v91
	v_rcp_f32_e32 v90, v90
	v_rcp_f32_e32 v91, v91
	v_add_f32_e32 v92, 1.0, v92
	v_add_f32_e32 v93, 1.0, v93
	v_rcp_f32_e32 v92, v92
	v_rcp_f32_e32 v93, v93
	v_pk_mul_f32 v[74:75], v[74:75], v[98:99] op_sel_hi:[1,0]
	v_pk_mul_f32 v[82:83], v[82:83], v[90:91]
	s_nop 0
	v_pk_mul_f32 v[82:83], v[74:75], v[82:83]
	v_pk_mul_f32 v[74:75], v[76:77], v[98:99] op_sel_hi:[1,0]
	v_pk_mul_f32 v[76:77], v[84:85], v[92:93]
	s_nop 0
	v_pk_mul_f32 v[84:85], v[74:75], v[76:77]
	v_cvt_pk_bf16_f32 v74, v78, v79
	v_mad_i64_i32 v[78:79], s[4:5], v204, s68, v[132:133]
	v_cvt_pk_bf16_f32 v75, v80, v81
	v_cvt_pk_bf16_f32 v76, v82, v83
	v_cvt_pk_bf16_f32 v77, v84, v85
	v_lshl_add_u64 v[78:79], v[78:79], 0, v[130:131]
	global_store_dwordx4 v[78:79], v[74:77], off
	s_andn2_b64 vcc, exec, s[6:7]
	s_cbranch_vccnz .LBB0_1030
	s_waitcnt vmcnt(4)
	global_store_dwordx4 v[248:249], v[146:149], off nt
	global_store_dwordx4 v[250:251], v[154:157], off nt
	global_store_dwordx4 v[252:253], v[150:153], off nt
	global_store_dwordx4 v[254:255], v[158:161], off nt
